# baseline (speedup 1.0000x reference)
; #define PG8_STAGE(bufoff, gbase, voff) do { _Pragma("unroll") for (int _i = 0; _i < 2; ++_i) \
;         __builtin_amdgcn_global_load_lds((const unsigned*)((const char*)(gbase) + (voff)[_i]), (LAS unsigned*)(lds + (bufoff) + ldsw + _i * 8192), 16, 0, 0); } while (0)
; #define PG8_LDA(dst, b, h) do { _Pragma("unroll") for (int m = 0; m < 4; ++m) _Pragma("unroll") for (int k = 0; k < 2; ++k) dst[m][k] = *(const LAS bf16x8*)(lds + PG8_SA(b, h) + aoff + m * 2048 + k * 1024); } while (0)
; #define PG8_LDB(dst, b, h) do { _Pragma("unroll") for (int n = 0; n < 2; ++n) _Pragma("unroll") for (int k = 0; k < 2; ++k) dst[n][k] = *(const LAS bf16x8*)(lds + PG8_SB(b, h) + boff + n * 2048 + k * 1024); } while (0)
; #define PG8_MMA(ai, bj, At, Bt) do { __builtin_amdgcn_s_setprio(1); _Pragma("unroll") for (int m = 0; m < 4; ++m) _Pragma("unroll") for (int n = 0; n < 2; ++n) _Pragma("unroll") for (int k = 0; k < 2; ++k) \
;         acc[ai][bj][m][n] = __builtin_amdgcn_mfma_f32_16x16x32_bf16(Bt[n][k], At[m][k], acc[ai][bj][m][n], 0, 0, 0); __builtin_amdgcn_s_setprio(0); } while (0)
; #define PG8_WAIT_V(n) asm volatile("s_waitcnt vmcnt(" #n ")" ::: "memory")
; #define PG8_WAIT_L(n) asm volatile("s_waitcnt lgkmcnt(" #n ")" ::: "memory")
; #define PG8_BAR __builtin_amdgcn_s_barrier()
; #define PG8_SCHED __builtin_amdgcn_sched_barrier(0)
; __device__ __forceinline__ void gemm_phase(LAS unsigned char* lds, const GemmD& g) {
;     ...
;             PG8_LDB(B1, 0, 1); PG8_STAGE(PG8_SB(0, 0), b2, voffB);
;             PG8_BAR; PG8_WAIT_L(0); PG8_MMA(0, 1, At, B1); PG8_BAR;
;             PG8_LDA(At, 0, 1); PG8_STAGE(PG8_SA(0, 0), a2, voffA);
;             PG8_BAR; PG8_WAIT_L(0); PG8_MMA(1, 0, At, B0); PG8_BAR; PG8_SCHED;
;             PG8_STAGE(PG8_SB(0, 1), b2 + hstep, voffB);
;             PG8_WAIT_V(6); PG8_BAR; PG8_MMA(1, 1, At, B1); PG8_BAR;
;             PG8_LDB(B0, 1, 0); PG8_SCHED; PG8_LDA(At, 1, 0); PG8_STAGE(PG8_SA(0, 1), a2 + hstep, voffA);
;             PG8_WAIT_L(8); PG8_BAR; PG8_WAIT_L(0); PG8_MMA(0, 0, At, B0); PG8_BAR; PG8_SCHED;
.Lkl_ptr_done:
	s_add_i32 s4, 0, 0x14000
	s_add_i32 s6, s6, s87
	s_mov_b32 m0, s6
	ds_read_b128 v[204:207], v245
	ds_read_b128 v[208:211], v245 offset:1024
	ds_read_b128 v[234:237], v245 offset:2048
	ds_read_b128 v[238:241], v245 offset:3072
	global_load_lds_dwordx4 v172, s[100:101]
	s_add_i32 m0, s6, 0x2000
	s_nop 0
	global_load_lds_dwordx4 v168, s[100:101]
	s_waitcnt lgkmcnt(0)
	s_barrier
	v_mfma_f32_16x16x32_bf16 v[118:121], v[204:207], v[152:155], v[118:121]
	v_mfma_f32_16x16x32_bf16 v[114:117], v[234:237], v[152:155], v[114:117]
	v_mfma_f32_16x16x32_bf16 v[102:105], v[204:207], v[160:163], v[102:105]
	v_mfma_f32_16x16x32_bf16 v[98:101], v[234:237], v[160:163], v[98:101]
	v_mfma_f32_16x16x32_bf16 v[86:89], v[204:207], v[188:191], v[86:89]
	v_mfma_f32_16x16x32_bf16 v[82:85], v[234:237], v[188:191], v[82:85]
	v_mfma_f32_16x16x32_bf16 v[70:73], v[204:207], v[196:199], v[70:73]
	v_mfma_f32_16x16x32_bf16 v[66:69], v[234:237], v[196:199], v[66:69]
	v_mfma_f32_16x16x32_bf16 v[118:121], v[208:211], v[156:159], v[118:121]
	v_mfma_f32_16x16x32_bf16 v[114:117], v[238:241], v[156:159], v[114:117]
	v_mfma_f32_16x16x32_bf16 v[102:105], v[208:211], v[184:187], v[102:105]
	v_mfma_f32_16x16x32_bf16 v[98:101], v[238:241], v[184:187], v[98:101]
	v_mfma_f32_16x16x32_bf16 v[86:89], v[208:211], v[192:195], v[86:89]
	v_mfma_f32_16x16x32_bf16 v[82:85], v[238:241], v[192:195], v[82:85]
	v_mfma_f32_16x16x32_bf16 v[70:73], v[208:211], v[200:203], v[70:73]
	v_mfma_f32_16x16x32_bf16 v[66:69], v[238:241], v[200:203], v[66:69]
	s_barrier
	s_mov_b32 m0, s2
	ds_read_b128 v[152:155], v233 offset:16384
	ds_read_b128 v[156:159], v233 offset:17408
	ds_read_b128 v[160:163], v233 offset:18432
	ds_read_b128 v[184:187], v233 offset:19456
	ds_read_b128 v[188:191], v233 offset:20480
	ds_read_b128 v[192:195], v233 offset:21504
	ds_read_b128 v[196:199], v233 offset:22528
	ds_read_b128 v[200:203], v233 offset:23552
	global_load_lds_dwordx4 v170, s[98:99]
	s_mov_b32 m0, s3
	s_nop 0
	global_load_lds_dwordx4 v166, s[98:99]
	s_waitcnt lgkmcnt(0)
	s_barrier
	v_mfma_f32_16x16x32_bf16 v[62:65], v[136:139], v[152:155], v[62:65]
	v_mfma_f32_16x16x32_bf16 v[58:61], v[144:147], v[152:155], v[58:61]
	v_mfma_f32_16x16x32_bf16 v[46:49], v[136:139], v[160:163], v[46:49]
	v_mfma_f32_16x16x32_bf16 v[42:45], v[144:147], v[160:163], v[42:45]
	v_mfma_f32_16x16x32_bf16 v[30:33], v[136:139], v[188:191], v[30:33]
	v_mfma_f32_16x16x32_bf16 v[26:29], v[144:147], v[188:191], v[26:29]
	v_mfma_f32_16x16x32_bf16 v[14:17], v[136:139], v[196:199], v[14:17]
	v_mfma_f32_16x16x32_bf16 v[10:13], v[144:147], v[196:199], v[10:13]
	v_mfma_f32_16x16x32_bf16 v[62:65], v[140:143], v[156:159], v[62:65]
	v_mfma_f32_16x16x32_bf16 v[58:61], v[148:151], v[156:159], v[58:61]
	v_mfma_f32_16x16x32_bf16 v[46:49], v[140:143], v[184:187], v[46:49]
	v_mfma_f32_16x16x32_bf16 v[42:45], v[148:151], v[184:187], v[42:45]
	v_mfma_f32_16x16x32_bf16 v[30:33], v[140:143], v[192:195], v[30:33]
	v_mfma_f32_16x16x32_bf16 v[26:29], v[148:151], v[192:195], v[26:29]
	v_mfma_f32_16x16x32_bf16 v[14:17], v[140:143], v[200:203], v[14:17]
	v_mfma_f32_16x16x32_bf16 v[10:13], v[148:151], v[200:203], v[10:13]
	s_barrier
	s_add_i32 s4, s4, s87
	s_mov_b32 m0, s4
	s_nop 0
	global_load_lds_dwordx4 v242, s[100:101]
	s_add_i32 m0, s4, 0x2000
	s_nop 0
	global_load_lds_dwordx4 v243, s[100:101]
	s_waitcnt vmcnt(6)
	s_mov_b32 m0, s64
	s_nop 0
	global_load_lds_dwordx4 v174, s[98:99]
	s_mov_b32 m0, s65
	s_nop 0
	global_load_lds_dwordx4 v176, s[98:99]
	s_barrier
	v_mfma_f32_16x16x32_bf16 v[54:57], v[204:207], v[152:155], v[54:57]
	v_mfma_f32_16x16x32_bf16 v[50:53], v[234:237], v[152:155], v[50:53]
	v_mfma_f32_16x16x32_bf16 v[38:41], v[204:207], v[160:163], v[38:41]
	v_mfma_f32_16x16x32_bf16 v[34:37], v[234:237], v[160:163], v[34:37]
	v_mfma_f32_16x16x32_bf16 v[22:25], v[204:207], v[188:191], v[22:25]
	v_mfma_f32_16x16x32_bf16 v[18:21], v[234:237], v[188:191], v[18:21]
	v_mfma_f32_16x16x32_bf16 v[6:9], v[204:207], v[196:199], v[6:9]
	v_mfma_f32_16x16x32_bf16 v[2:5], v[234:237], v[196:199], v[2:5]
	v_mfma_f32_16x16x32_bf16 v[54:57], v[208:211], v[156:159], v[54:57]
	v_mfma_f32_16x16x32_bf16 v[50:53], v[238:241], v[156:159], v[50:53]
	v_mfma_f32_16x16x32_bf16 v[38:41], v[208:211], v[184:187], v[38:41]
	v_mfma_f32_16x16x32_bf16 v[34:37], v[238:241], v[184:187], v[34:37]
	v_mfma_f32_16x16x32_bf16 v[22:25], v[208:211], v[192:195], v[22:25]
	v_mfma_f32_16x16x32_bf16 v[18:21], v[238:241], v[192:195], v[18:21]
	v_mfma_f32_16x16x32_bf16 v[6:9], v[208:211], v[200:203], v[6:9]
	v_mfma_f32_16x16x32_bf16 v[2:5], v[238:241], v[200:203], v[2:5]
	s_barrier
	s_add_i32 s4, 0, 0x18000
	ds_read_b128 v[136:139], v246
	ds_read_b128 v[140:143], v246 offset:1024
	ds_read_b128 v[144:147], v246 offset:2048
	ds_read_b128 v[148:151], v246 offset:3072
	ds_read_b128 v[152:155], v233 offset:32768
	ds_read_b128 v[156:159], v233 offset:33792
	ds_read_b128 v[160:163], v233 offset:34816
	ds_read_b128 v[184:187], v233 offset:35840
	ds_read_b128 v[188:191], v233 offset:36864
	ds_read_b128 v[192:195], v233 offset:37888
	ds_read_b128 v[196:199], v233 offset:38912
	ds_read_b128 v[200:203], v233 offset:39936
	s_waitcnt lgkmcnt(8)
	s_barrier
; #define PG8_STAGE(bufoff, gbase, voff) do { _Pragma("unroll") for (int _i = 0; _i < 2; ++_i) \
;         __builtin_amdgcn_global_load_lds((const unsigned*)((const char*)(gbase) + (voff)[_i]), (LAS unsigned*)(lds + (bufoff) + ldsw + _i * 8192), 16, 0, 0); } while (0)
; #define PG8_LDA(dst, b, h) do { _Pragma("unroll") for (int m = 0; m < 4; ++m) _Pragma("unroll") for (int k = 0; k < 2; ++k) dst[m][k] = *(const LAS bf16x8*)(lds + PG8_SA(b, h) + aoff + m * 2048 + k * 1024); } while (0)
; #define PG8_LDB(dst, b, h) do { _Pragma("unroll") for (int n = 0; n < 2; ++n) _Pragma("unroll") for (int k = 0; k < 2; ++k) dst[n][k] = *(const LAS bf16x8*)(lds + PG8_SB(b, h) + boff + n * 2048 + k * 1024); } while (0)
; #define PG8_MMA(ai, bj, At, Bt) do { __builtin_amdgcn_s_setprio(1); _Pragma("unroll") for (int m = 0; m < 4; ++m) _Pragma("unroll") for (int n = 0; n < 2; ++n) _Pragma("unroll") for (int k = 0; k < 2; ++k) \
;         acc[ai][bj][m][n] = __builtin_amdgcn_mfma_f32_16x16x32_bf16(Bt[n][k], At[m][k], acc[ai][bj][m][n], 0, 0, 0); __builtin_amdgcn_s_setprio(0); } while (0)
; #define PG8_WAIT_V(n) asm volatile("s_waitcnt vmcnt(" #n ")" ::: "memory")
; #define PG8_WAIT_L(n) asm volatile("s_waitcnt lgkmcnt(" #n ")" ::: "memory")
; #define PG8_BAR __builtin_amdgcn_s_barrier()
; #define PG8_SCHED __builtin_amdgcn_sched_barrier(0)
; __device__ __forceinline__ void gemm_epilogue(const GemmD& g, const f32x4 (&acc)[2][2][4][2], const Unit& u, int wr, int wc, int fr, int fq) {
;     const int row0 = u.pm * BM + wr * 64 + fr;
;     const int mode = g.mode;
;     if (u.part >= 0) {
; __device__ __forceinline__ void gemm_phase(LAS unsigned char* lds, const GemmD& g) {
;     ...
;             PG8_WAIT_L(8); PG8_BAR; PG8_WAIT_L(0); PG8_MMA(0, 0, At, B0); PG8_BAR; PG8_SCHED;
;             PG8_LDB(B1, 1, 1); PG8_STAGE(PG8_SB(1, 0), b3, voffB);
;             PG8_BAR; PG8_WAIT_L(0); PG8_MMA(0, 1, At, B1); PG8_BAR;
;             PG8_LDA(At, 1, 1); PG8_STAGE(PG8_SA(1, 0), a3, voffA);
;             PG8_BAR; PG8_WAIT_L(0); PG8_MMA(1, 0, At, B0); PG8_BAR; PG8_SCHED;
;             PG8_STAGE(PG8_SB(1, 1), b3 + hstep, voffB);
;             PG8_WAIT_V(6); PG8_BAR; PG8_MMA(1, 1, At, B1); PG8_BAR;
;         }
	s_waitcnt lgkmcnt(0)
	v_mfma_f32_16x16x32_bf16 v[126:129], v[136:139], v[152:155], v[126:129]
	v_mfma_f32_16x16x32_bf16 v[122:125], v[144:147], v[152:155], v[122:125]
	v_mfma_f32_16x16x32_bf16 v[110:113], v[136:139], v[160:163], v[110:113]
	v_mfma_f32_16x16x32_bf16 v[106:109], v[144:147], v[160:163], v[106:109]
	v_mfma_f32_16x16x32_bf16 v[94:97], v[136:139], v[188:191], v[94:97]
	v_mfma_f32_16x16x32_bf16 v[90:93], v[144:147], v[188:191], v[90:93]
	v_mfma_f32_16x16x32_bf16 v[78:81], v[136:139], v[196:199], v[78:81]
	v_mfma_f32_16x16x32_bf16 v[74:77], v[144:147], v[196:199], v[74:77]
	v_mfma_f32_16x16x32_bf16 v[126:129], v[140:143], v[156:159], v[126:129]
	v_mfma_f32_16x16x32_bf16 v[122:125], v[148:151], v[156:159], v[122:125]
	v_mfma_f32_16x16x32_bf16 v[110:113], v[140:143], v[184:187], v[110:113]
	v_mfma_f32_16x16x32_bf16 v[106:109], v[148:151], v[184:187], v[106:109]
	v_mfma_f32_16x16x32_bf16 v[94:97], v[140:143], v[192:195], v[94:97]
	v_mfma_f32_16x16x32_bf16 v[90:93], v[148:151], v[192:195], v[90:93]
	v_mfma_f32_16x16x32_bf16 v[78:81], v[140:143], v[200:203], v[78:81]
	v_mfma_f32_16x16x32_bf16 v[74:77], v[148:151], v[200:203], v[74:77]
	s_barrier
	s_add_i32 s6, 0, 0x1c000
	s_add_i32 s4, s4, s87
	ds_read_b128 v[204:207], v247
	ds_read_b128 v[208:211], v247 offset:1024
	ds_read_b128 v[234:237], v247 offset:2048
	ds_read_b128 v[238:241], v247 offset:3072
	s_add_u32 s100, s100, 0x80
	s_addc_u32 s101, s101, 0
	s_mov_b32 m0, s4
	s_nop 0
	global_load_lds_dwordx4 v172, s[100:101]
	s_add_i32 m0, s4, 0x2000
	s_nop 0
	global_load_lds_dwordx4 v168, s[100:101]
	s_waitcnt lgkmcnt(0)
	s_barrier
	v_mfma_f32_16x16x32_bf16 v[118:121], v[204:207], v[152:155], v[118:121]
	v_mfma_f32_16x16x32_bf16 v[114:117], v[234:237], v[152:155], v[114:117]
	v_mfma_f32_16x16x32_bf16 v[102:105], v[204:207], v[160:163], v[102:105]
	v_mfma_f32_16x16x32_bf16 v[98:101], v[234:237], v[160:163], v[98:101]
	v_mfma_f32_16x16x32_bf16 v[86:89], v[204:207], v[188:191], v[86:89]
	v_mfma_f32_16x16x32_bf16 v[82:85], v[234:237], v[188:191], v[82:85]
	v_mfma_f32_16x16x32_bf16 v[70:73], v[204:207], v[196:199], v[70:73]
	v_mfma_f32_16x16x32_bf16 v[66:69], v[234:237], v[196:199], v[66:69]
	v_mfma_f32_16x16x32_bf16 v[118:121], v[208:211], v[156:159], v[118:121]
	v_mfma_f32_16x16x32_bf16 v[114:117], v[238:241], v[156:159], v[114:117]
	v_mfma_f32_16x16x32_bf16 v[102:105], v[208:211], v[184:187], v[102:105]
	v_mfma_f32_16x16x32_bf16 v[98:101], v[238:241], v[184:187], v[98:101]
	v_mfma_f32_16x16x32_bf16 v[86:89], v[208:211], v[192:195], v[86:89]
	v_mfma_f32_16x16x32_bf16 v[82:85], v[238:241], v[192:195], v[82:85]
	v_mfma_f32_16x16x32_bf16 v[70:73], v[208:211], v[200:203], v[70:73]
	v_mfma_f32_16x16x32_bf16 v[66:69], v[238:241], v[200:203], v[66:69]
	s_barrier
	s_mov_b32 m0, s28
	s_add_u32 s98, s98, 0x80
	s_addc_u32 s99, s99, 0
	ds_read_b128 v[152:155], v233 offset:49152
	ds_read_b128 v[156:159], v233 offset:50176
	ds_read_b128 v[160:163], v233 offset:51200
	ds_read_b128 v[184:187], v233 offset:52224
	ds_read_b128 v[188:191], v233 offset:53248
	ds_read_b128 v[192:195], v233 offset:54272
	ds_read_b128 v[196:199], v233 offset:55296
	ds_read_b128 v[200:203], v233 offset:56320
	global_load_lds_dwordx4 v170, s[98:99]
	s_mov_b32 m0, s29
	s_nop 0
	global_load_lds_dwordx4 v166, s[98:99]
	s_waitcnt lgkmcnt(0)
	s_barrier
	v_mfma_f32_16x16x32_bf16 v[62:65], v[136:139], v[152:155], v[62:65]
	v_mfma_f32_16x16x32_bf16 v[58:61], v[144:147], v[152:155], v[58:61]
	v_mfma_f32_16x16x32_bf16 v[46:49], v[136:139], v[160:163], v[46:49]
	v_mfma_f32_16x16x32_bf16 v[42:45], v[144:147], v[160:163], v[42:45]
	v_mfma_f32_16x16x32_bf16 v[30:33], v[136:139], v[188:191], v[30:33]
	v_mfma_f32_16x16x32_bf16 v[26:29], v[144:147], v[188:191], v[26:29]
	v_mfma_f32_16x16x32_bf16 v[14:17], v[136:139], v[196:199], v[14:17]
	v_mfma_f32_16x16x32_bf16 v[10:13], v[144:147], v[196:199], v[10:13]
	v_mfma_f32_16x16x32_bf16 v[62:65], v[140:143], v[156:159], v[62:65]
	v_mfma_f32_16x16x32_bf16 v[58:61], v[148:151], v[156:159], v[58:61]
	v_mfma_f32_16x16x32_bf16 v[46:49], v[140:143], v[184:187], v[46:49]
	v_mfma_f32_16x16x32_bf16 v[42:45], v[148:151], v[184:187], v[42:45]
	v_mfma_f32_16x16x32_bf16 v[30:33], v[140:143], v[192:195], v[30:33]
	v_mfma_f32_16x16x32_bf16 v[26:29], v[148:151], v[192:195], v[26:29]
	v_mfma_f32_16x16x32_bf16 v[14:17], v[140:143], v[200:203], v[14:17]
	v_mfma_f32_16x16x32_bf16 v[10:13], v[148:151], v[200:203], v[10:13]
	s_barrier
	s_add_i32 s4, s6, s87
	s_mov_b32 m0, s4
	s_nop 0
	global_load_lds_dwordx4 v242, s[100:101]
	s_add_i32 m0, s4, 0x2000
	s_nop 0
	global_load_lds_dwordx4 v243, s[100:101]
	s_add_u32 s100, s100, 0x80
	s_addc_u32 s101, s101, 0
	s_mov_b32 s4, s5
	s_waitcnt vmcnt(6)
	s_barrier
	v_mfma_f32_16x16x32_bf16 v[54:57], v[204:207], v[152:155], v[54:57]
	v_mfma_f32_16x16x32_bf16 v[50:53], v[234:237], v[152:155], v[50:53]
	v_mfma_f32_16x16x32_bf16 v[38:41], v[204:207], v[160:163], v[38:41]
	v_mfma_f32_16x16x32_bf16 v[34:37], v[234:237], v[160:163], v[34:37]
	v_mfma_f32_16x16x32_bf16 v[22:25], v[204:207], v[188:191], v[22:25]
	v_mfma_f32_16x16x32_bf16 v[18:21], v[234:237], v[188:191], v[18:21]
	v_mfma_f32_16x16x32_bf16 v[6:9], v[204:207], v[196:199], v[6:9]
	v_mfma_f32_16x16x32_bf16 v[2:5], v[234:237], v[196:199], v[2:5]
	v_mfma_f32_16x16x32_bf16 v[54:57], v[208:211], v[156:159], v[54:57]
	v_mfma_f32_16x16x32_bf16 v[50:53], v[238:241], v[156:159], v[50:53]
	v_mfma_f32_16x16x32_bf16 v[38:41], v[208:211], v[184:187], v[38:41]
	v_mfma_f32_16x16x32_bf16 v[34:37], v[238:241], v[184:187], v[34:37]
	v_mfma_f32_16x16x32_bf16 v[22:25], v[208:211], v[192:195], v[22:25]
	v_mfma_f32_16x16x32_bf16 v[18:21], v[238:241], v[192:195], v[18:21]
	v_mfma_f32_16x16x32_bf16 v[6:9], v[208:211], v[200:203], v[6:9]
	v_mfma_f32_16x16x32_bf16 v[2:5], v[238:241], v[200:203], v[2:5]
	s_barrier
	s_cbranch_vccz .LBB0_145
	v_lshl_add_u32 v184, s56, 8, v228
	s_cmp_lt_i32 s66, 0
	s_mov_b64 s[4:5], -1
	s_cbranch_scc0 .LBB0_704
